# attention work queue: next item index fetched at the start of the item epilogue (hidden behind the epilogue) instead of one whole item ahead
# speedup vs baseline: 1.0379x; 1.0379x over previous
; __device__ __forceinline__ void attn_item(const Args& A, LAS unsigned char* lds, int b, int h, int qb, float lam) {
;     ...
;     float inv[2];
; #pragma unroll
;     for (int p = 0; p < 2; ++p) { const float lt = xrow_sum(lrun[p]); inv[p] = 1.f / lt; }
;     float ss = 0.f;
; #pragma unroll
;     for (int vt = 0; vt < 8; ++vt)
; #pragma unroll
;         for (int r = 0; r < 4; ++r) { const float ov = o[0][vt][r] * inv[0] - lam * (o[1][vt][r] * inv[1]); o[0][vt][r] = ov; ss += ov * ov; }
;     ss = xrow_sum(ss);
;     const float rstd = rsqrtf(ss * (1.f / 128.f) + 1e-6f) * 0.8f;
.LBB0_313:
	s_or_b64 exec, exec, s[72:73]
	s_and_saveexec_b64 s[0:1], s[18:19]
	s_cbranch_execz .Lqf_next_skip
	v_mov_b32_e32 v237, 1
	global_atomic_add v237, v129, v237, s[50:51] sc0
.Lqf_next_skip:
	s_or_b64 exec, exec, s[0:1]
	v_mov_b32_e32 v64, v133
	s_nop 1
	v_permlane16_swap_b32_e32 v133, v64
	v_add_f32_e32 v64, v133, v64
	v_mov_b32_e32 v65, v64
	s_nop 1
	v_permlane32_swap_b32_e32 v64, v65
	v_add_f32_e32 v64, v64, v65
	v_div_scale_f32 v65, s[0:1], v64, v64, 1.0
	v_rcp_f32_e32 v66, v65
	v_ashrrev_i32_e32 v133, 31, v132
	s_barrier
	v_fma_f32 v67, -v65, v66, 1.0
	v_fmac_f32_e32 v66, v67, v66
	v_div_scale_f32 v67, vcc, 1.0, v64, 1.0
	v_mul_f32_e32 v68, v67, v66
	v_fma_f32 v69, -v65, v68, v67
	v_fmac_f32_e32 v68, v69, v66
	v_fma_f32 v65, -v65, v68, v67
	v_mov_b32_e32 v67, v144
	s_nop 1
	v_permlane16_swap_b32_e32 v144, v67
	v_add_f32_e32 v67, v144, v67
	v_mov_b32_e32 v69, v67
	s_nop 1
	v_permlane32_swap_b32_e32 v67, v69
	v_add_f32_e32 v67, v67, v69
	v_div_scale_f32 v69, s[0:1], v67, v67, 1.0
	v_rcp_f32_e32 v70, v69
	v_div_fmas_f32 v65, v65, v66, v68
	v_div_fixup_f32 v68, v65, v64, 1.0
	v_fma_f32 v64, -v69, v70, 1.0
	v_fmac_f32_e32 v70, v64, v70
	v_div_scale_f32 v64, vcc, 1.0, v67, 1.0
	v_mul_f32_e32 v65, v64, v70
	v_fma_f32 v66, -v69, v65, v64
	v_fmac_f32_e32 v65, v66, v70
	v_fma_f32 v64, -v69, v65, v64
	v_div_fmas_f32 v64, v64, v70, v65
	v_div_fixup_f32 v70, v64, v67, 1.0
	v_lshl_add_u64 v[64:65], v[132:133], 0, s[62:63]
	v_lshlrev_b64 v[64:65], 11, v[64:65]
	v_lshlrev_b32_e32 v69, 2, v143
	v_lshl_add_u64 v[72:73], s[50:51], 0, v[64:65]
	global_load_dwordx4 v[64:67], v69, s[80:81]
	global_load_dwordx4 v[240:243], v69, s[80:81] offset:64
	global_load_dwordx4 v[244:247], v69, s[80:81] offset:128
	global_load_dwordx4 v[248:251], v69, s[80:81] offset:192
	global_load_dwordx4 v[252:255], v69, s[80:81] offset:256
	v_pk_mul_f32 v[56:57], v[56:57], v[70:71] op_sel_hi:[1,0]
	v_pk_mul_f32 v[58:59], v[58:59], v[70:71] op_sel_hi:[1,0]
	v_pk_mul_f32 v[56:57], v[130:131], v[56:57]
	v_pk_mul_f32 v[58:59], v[130:131], v[58:59]
	v_pk_fma_f32 v[56:57], v[60:61], v[68:69], v[56:57] op_sel_hi:[1,0,1] neg_lo:[0,0,1] neg_hi:[0,0,1]
	v_pk_fma_f32 v[58:59], v[62:63], v[68:69], v[58:59] op_sel_hi:[1,0,1] neg_lo:[0,0,1] neg_hi:[0,0,1]
	v_mul_f32_e32 v60, v57, v57
	v_pk_fma_f32 v[60:61], v[56:57], v[56:57], v[60:61] op_sel_hi:[1,1,0]
	v_pk_mul_f32 v[48:49], v[48:49], v[70:71] op_sel_hi:[1,0]
	v_pk_fma_f32 v[60:61], v[58:59], v[58:59], v[60:61]
	v_mul_f32_e32 v62, v59, v59
	v_pk_mul_f32 v[50:51], v[50:51], v[70:71] op_sel_hi:[1,0]
	v_pk_mul_f32 v[48:49], v[130:131], v[48:49]
	v_pk_add_f32 v[60:61], v[62:63], v[60:61] op_sel_hi:[0,1]
	v_pk_mul_f32 v[50:51], v[130:131], v[50:51]
	v_pk_fma_f32 v[48:49], v[52:53], v[68:69], v[48:49] op_sel_hi:[1,0,1] neg_lo:[0,0,1] neg_hi:[0,0,1]
	v_pk_fma_f32 v[50:51], v[54:55], v[68:69], v[50:51] op_sel_hi:[1,0,1] neg_lo:[0,0,1] neg_hi:[0,0,1]
	v_pk_fma_f32 v[52:53], v[48:49], v[48:49], v[60:61]
	v_mul_f32_e32 v54, v49, v49
	v_pk_add_f32 v[52:53], v[54:55], v[52:53] op_sel_hi:[0,1]
	v_pk_mul_f32 v[40:41], v[40:41], v[70:71] op_sel_hi:[1,0]
	v_pk_fma_f32 v[52:53], v[50:51], v[50:51], v[52:53]
	v_mul_f32_e32 v54, v51, v51
	v_pk_mul_f32 v[42:43], v[42:43], v[70:71] op_sel_hi:[1,0]
	v_pk_mul_f32 v[40:41], v[130:131], v[40:41]
	v_pk_add_f32 v[52:53], v[54:55], v[52:53] op_sel_hi:[0,1]
	v_pk_mul_f32 v[42:43], v[130:131], v[42:43]
	v_pk_fma_f32 v[40:41], v[44:45], v[68:69], v[40:41] op_sel_hi:[1,0,1] neg_lo:[0,0,1] neg_hi:[0,0,1]
	v_pk_fma_f32 v[42:43], v[46:47], v[68:69], v[42:43] op_sel_hi:[1,0,1] neg_lo:[0,0,1] neg_hi:[0,0,1]
	v_pk_fma_f32 v[44:45], v[40:41], v[40:41], v[52:53]
	v_mul_f32_e32 v46, v41, v41
	v_pk_add_f32 v[44:45], v[46:47], v[44:45] op_sel_hi:[0,1]
	v_pk_mul_f32 v[32:33], v[32:33], v[70:71] op_sel_hi:[1,0]
	v_pk_fma_f32 v[44:45], v[42:43], v[42:43], v[44:45]
	v_mul_f32_e32 v46, v43, v43
	v_pk_mul_f32 v[34:35], v[34:35], v[70:71] op_sel_hi:[1,0]
	v_pk_mul_f32 v[32:33], v[130:131], v[32:33]
	v_pk_add_f32 v[44:45], v[46:47], v[44:45] op_sel_hi:[0,1]
	v_pk_mul_f32 v[34:35], v[130:131], v[34:35]
	v_pk_fma_f32 v[32:33], v[36:37], v[68:69], v[32:33] op_sel_hi:[1,0,1] neg_lo:[0,0,1] neg_hi:[0,0,1]
	v_pk_fma_f32 v[34:35], v[38:39], v[68:69], v[34:35] op_sel_hi:[1,0,1] neg_lo:[0,0,1] neg_hi:[0,0,1]
	v_pk_fma_f32 v[36:37], v[32:33], v[32:33], v[44:45]
	v_mul_f32_e32 v38, v33, v33
	v_pk_add_f32 v[36:37], v[38:39], v[36:37] op_sel_hi:[0,1]
	v_pk_mul_f32 v[24:25], v[24:25], v[70:71] op_sel_hi:[1,0]
	v_pk_fma_f32 v[36:37], v[34:35], v[34:35], v[36:37]
	v_mul_f32_e32 v38, v35, v35
	v_pk_mul_f32 v[26:27], v[26:27], v[70:71] op_sel_hi:[1,0]
	v_pk_mul_f32 v[24:25], v[130:131], v[24:25]
	v_pk_add_f32 v[36:37], v[38:39], v[36:37] op_sel_hi:[0,1]
	v_pk_mul_f32 v[26:27], v[130:131], v[26:27]
	v_pk_fma_f32 v[24:25], v[28:29], v[68:69], v[24:25] op_sel_hi:[1,0,1] neg_lo:[0,0,1] neg_hi:[0,0,1]
	v_pk_fma_f32 v[26:27], v[30:31], v[68:69], v[26:27] op_sel_hi:[1,0,1] neg_lo:[0,0,1] neg_hi:[0,0,1]
	v_pk_fma_f32 v[28:29], v[24:25], v[24:25], v[36:37]
	v_mul_f32_e32 v30, v25, v25
	v_pk_add_f32 v[28:29], v[30:31], v[28:29] op_sel_hi:[0,1]
	v_pk_mul_f32 v[12:13], v[12:13], v[70:71] op_sel_hi:[1,0]
	v_pk_fma_f32 v[28:29], v[26:27], v[26:27], v[28:29]
	v_mul_f32_e32 v30, v27, v27
	v_pk_mul_f32 v[14:15], v[14:15], v[70:71] op_sel_hi:[1,0]
	v_pk_mul_f32 v[12:13], v[130:131], v[12:13]
	v_pk_add_f32 v[28:29], v[30:31], v[28:29] op_sel_hi:[0,1]
	v_pk_mul_f32 v[14:15], v[130:131], v[14:15]
; __device__ __forceinline__ unsigned pk2(float lo, float hi) { const f32x2 v = {lo, hi}; const bf16x2_t b = __builtin_convertvector(v, bf16x2_t); return __builtin_bit_cast(unsigned, b); }
; __device__ __forceinline__ void attn_item(const Args& A, LAS unsigned char* lds, int b, int h, int qb, float lam) {
;     ...
;         for (int r = 0; r < 4; ++r) { const float ov = o[0][vt][r] * inv[0] - lam * (o[1][vt][r] * inv[1]); o[0][vt][r] = ov; ss += ov * ov; }
;     ss = xrow_sum(ss);
;     const float rstd = rsqrtf(ss * (1.f / 128.f) + 1e-6f) * 0.8f;
;     bf16_t* op = ACT + (rowbase + qabs) * 1024 + 512 + h * 128 + 4 * g;
; #pragma unroll
;     for (int vt = 0; vt < 8; ++vt) { const f32x4 gn = *(const f32x4*)(A.dnorm_g + 16 * vt + 4 * g);
;         u32x2 wv; wv.x = pk2(o[0][vt][0] * rstd * gn[0], o[0][vt][1] * rstd * gn[1]); wv.y = pk2(o[0][vt][2] * rstd * gn[2], o[0][vt][3] * rstd * gn[3]);
;         *(u32x2*)(op + 16 * vt) = wv; }
	v_pk_fma_f32 v[12:13], v[20:21], v[68:69], v[12:13] op_sel_hi:[1,0,1] neg_lo:[0,0,1] neg_hi:[0,0,1]
	v_pk_fma_f32 v[14:15], v[22:23], v[68:69], v[14:15] op_sel_hi:[1,0,1] neg_lo:[0,0,1] neg_hi:[0,0,1]
	v_pk_fma_f32 v[20:21], v[12:13], v[12:13], v[28:29]
	v_mul_f32_e32 v22, v13, v13
	v_pk_add_f32 v[20:21], v[22:23], v[20:21] op_sel_hi:[0,1]
	v_pk_mul_f32 v[16:17], v[16:17], v[70:71] op_sel_hi:[1,0]
	v_pk_fma_f32 v[20:21], v[14:15], v[14:15], v[20:21]
	v_mul_f32_e32 v22, v15, v15
	v_pk_mul_f32 v[18:19], v[18:19], v[70:71] op_sel_hi:[1,0]
	v_pk_mul_f32 v[16:17], v[130:131], v[16:17]
	v_pk_add_f32 v[20:21], v[22:23], v[20:21] op_sel_hi:[0,1]
	v_pk_mul_f32 v[18:19], v[130:131], v[18:19]
	v_pk_fma_f32 v[8:9], v[8:9], v[68:69], v[16:17] op_sel_hi:[1,0,1] neg_lo:[0,0,1] neg_hi:[0,0,1]
	v_pk_mul_f32 v[6:7], v[6:7], v[70:71] op_sel_hi:[1,0]
	v_pk_fma_f32 v[10:11], v[10:11], v[68:69], v[18:19] op_sel_hi:[1,0,1] neg_lo:[0,0,1] neg_hi:[0,0,1]
	v_pk_fma_f32 v[16:17], v[8:9], v[8:9], v[20:21]
	v_mul_f32_e32 v18, v9, v9
	v_pk_mul_f32 v[6:7], v[130:131], v[6:7]
	v_pk_add_f32 v[16:17], v[18:19], v[16:17] op_sel_hi:[0,1]
	v_pk_fma_f32 v[6:7], v[2:3], v[68:69], v[6:7] op_sel_hi:[1,0,1] neg_lo:[0,0,1] neg_hi:[0,0,1]
	v_pk_mul_f32 v[2:3], v[4:5], v[70:71] op_sel_hi:[1,0]
	v_pk_fma_f32 v[16:17], v[10:11], v[10:11], v[16:17]
	v_mul_f32_e32 v18, v11, v11
	v_pk_mul_f32 v[2:3], v[130:131], v[2:3]
	v_pk_add_f32 v[16:17], v[18:19], v[16:17] op_sel_hi:[0,1]
	v_pk_fma_f32 v[4:5], v[0:1], v[68:69], v[2:3] op_sel_hi:[1,0,1] neg_lo:[0,0,1] neg_hi:[0,0,1]
	s_lshl_b32 s62, s91, 1
	v_pk_fma_f32 v[0:1], v[4:5], v[4:5], v[16:17]
	v_mul_f32_e32 v2, v5, v5
	v_pk_add_f32 v[0:1], v[2:3], v[0:1] op_sel_hi:[0,1]
	v_pk_fma_f32 v[0:1], v[6:7], v[6:7], v[0:1]
	v_mul_f32_e32 v2, v7, v7
	v_pk_add_f32 v[0:1], v[2:3], v[0:1] op_sel_hi:[0,1]
	v_mov_b32_e32 v1, v0
	s_nop 1
	v_permlane16_swap_b32_e32 v0, v1
	v_add_f32_e32 v0, v0, v1
	v_mov_b32_e32 v1, v0
	s_nop 1
	v_permlane32_swap_b32_e32 v0, v1
	v_add_f32_e32 v0, v0, v1
	v_fmamk_f32 v0, v0, 0x3c000000, v140
	v_mul_f32_e32 v1, 0x4b800000, v0
	v_cmp_gt_f32_e32 vcc, s89, v0
	v_lshlrev_b32_e32 v128, 1, v143
	s_mov_b64 s[0:1], 0
	v_cndmask_b32_e32 v0, v0, v1, vcc
	v_rsq_f32_e32 v2, v0
	v_lshl_add_u64 v[0:1], v[72:73], 0, s[62:63]
	v_lshl_add_u64 v[16:17], v[0:1], 0, v[128:129]
	v_mul_f32_e32 v0, 0x45800000, v2
	v_cndmask_b32_e32 v0, v2, v0, vcc
	v_mul_f32_e32 v18, 0x3f4ccccd, v0
	v_pk_mul_f32 v[0:1], v[56:57], v[18:19] op_sel_hi:[1,0]
	v_pk_mul_f32 v[2:3], v[58:59], v[18:19] op_sel_hi:[1,0]
	s_waitcnt vmcnt(0)
	v_add_co_u32_e32 v238, vcc, s90, v16
	s_nop 1
	v_addc_co_u32_e32 v239, vcc, 0, v17, vcc
	v_lshl_add_u64 v[16:17], v[16:17], 0, s[68:69]
	v_pk_mul_f32 v[20:21], v[48:49], v[18:19] op_sel_hi:[1,0]
	v_pk_mul_f32 v[22:23], v[50:51], v[18:19] op_sel_hi:[1,0]
	v_pk_mul_f32 v[0:1], v[240:241], v[20:21]
	v_pk_mul_f32 v[2:3], v[242:243], v[22:23]
	v_cvt_pk_bf16_f32 v0, v0, v1
	v_cvt_pk_bf16_f32 v1, v2, v3
	global_store_dwordx2 v[16:17], v[0:1], off offset:32
	s_nop 1
	v_pk_mul_f32 v[20:21], v[40:41], v[18:19] op_sel_hi:[1,0]
	v_pk_mul_f32 v[22:23], v[42:43], v[18:19] op_sel_hi:[1,0]
	v_pk_mul_f32 v[0:1], v[244:245], v[20:21]
	v_pk_mul_f32 v[2:3], v[246:247], v[22:23]
	v_cvt_pk_bf16_f32 v0, v0, v1
	v_cvt_pk_bf16_f32 v1, v2, v3
	global_store_dwordx2 v[16:17], v[0:1], off offset:64
	s_nop 1
	v_pk_mul_f32 v[20:21], v[32:33], v[18:19] op_sel_hi:[1,0]
	v_pk_mul_f32 v[22:23], v[34:35], v[18:19] op_sel_hi:[1,0]
	v_pk_mul_f32 v[0:1], v[248:249], v[20:21]
	v_pk_mul_f32 v[2:3], v[250:251], v[22:23]
	v_cvt_pk_bf16_f32 v0, v0, v1
	v_cvt_pk_bf16_f32 v1, v2, v3
	global_store_dwordx2 v[16:17], v[0:1], off offset:96
	s_nop 1
	global_load_dwordx4 v[240:243], v69, s[80:81] offset:320
	global_load_dwordx4 v[244:247], v69, s[80:81] offset:384
	global_load_dwordx4 v[248:251], v69, s[80:81] offset:448
	v_pk_mul_f32 v[20:21], v[24:25], v[18:19] op_sel_hi:[1,0]
	v_pk_mul_f32 v[22:23], v[26:27], v[18:19] op_sel_hi:[1,0]
	v_pk_mul_f32 v[0:1], v[252:253], v[20:21]
	v_pk_mul_f32 v[2:3], v[254:255], v[22:23]
	v_cvt_pk_bf16_f32 v0, v0, v1
	v_cvt_pk_bf16_f32 v1, v2, v3
	global_store_dwordx2 v[16:17], v[0:1], off offset:128
	s_nop 1
	v_pk_mul_f32 v[20:21], v[56:57], v[18:19] op_sel_hi:[1,0]
	v_pk_mul_f32 v[22:23], v[58:59], v[18:19] op_sel_hi:[1,0]
	v_pk_mul_f32 v[0:1], v[64:65], v[20:21]
	v_pk_mul_f32 v[2:3], v[66:67], v[22:23]
	v_cvt_pk_bf16_f32 v0, v0, v1
	v_cvt_pk_bf16_f32 v1, v2, v3
	global_store_dwordx2 v[238:239], v[0:1], off offset:1024
	s_nop 1
	v_pk_mul_f32 v[12:13], v[12:13], v[18:19] op_sel_hi:[1,0]
	v_pk_mul_f32 v[14:15], v[14:15], v[18:19] op_sel_hi:[1,0]
	v_pk_mul_f32 v[8:9], v[8:9], v[18:19] op_sel_hi:[1,0]
	v_pk_mul_f32 v[10:11], v[10:11], v[18:19] op_sel_hi:[1,0]
	v_pk_mul_f32 v[4:5], v[4:5], v[18:19] op_sel_hi:[1,0]
	v_pk_mul_f32 v[6:7], v[6:7], v[18:19] op_sel_hi:[1,0]
	s_waitcnt vmcnt(0)
	v_pk_mul_f32 v[0:1], v[12:13], v[240:241]
	v_pk_mul_f32 v[2:3], v[14:15], v[242:243]
	v_cvt_pk_bf16_f32 v0, v0, v1
	v_cvt_pk_bf16_f32 v1, v2, v3
	global_store_dwordx2 v[16:17], v[0:1], off offset:160
	s_nop 1
	v_pk_mul_f32 v[0:1], v[8:9], v[244:245]
	v_pk_mul_f32 v[2:3], v[10:11], v[246:247]
	v_cvt_pk_bf16_f32 v0, v0, v1
	v_cvt_pk_bf16_f32 v1, v2, v3
	global_store_dwordx2 v[16:17], v[0:1], off offset:192
	s_nop 1
	v_pk_mul_f32 v[0:1], v[4:5], v[248:249]
	v_pk_mul_f32 v[2:3], v[6:7], v[250:251]
	v_cvt_pk_bf16_f32 v0, v0, v1
	v_cvt_pk_bf16_f32 v1, v2, v3
	global_store_dwordx2 v[16:17], v[0:1], off offset:224
	s_nop 1
